# attention item epilogue: the eight gain-quad loads issued together up front instead of a load/wait/store ladder
# speedup vs baseline: 1.0020x; 1.0020x over previous
; __device__ __forceinline__ void attn_phase(const Params& P, LAS unsigned char* lds, int tid, int wid, int lane) {
;     ...
;         l0 += __shfl_xor(l0, 16); l0 += __shfl_xor(l0, 32); l1 += __shfl_xor(l1, 16); l1 += __shfl_xor(l1, 32);
;         const float inv0 = __builtin_amdgcn_rcpf(l0), inv1 = lam * __builtin_amdgcn_rcpf(l1); float ss = 0.f;
; #pragma unroll
;         for (int dt = 0; dt < 8; ++dt) { O[0][dt] = O[0][dt] * inv0 - O[1][dt] * inv1; ss += (O[0][dt][0] * O[0][dt][0] + O[0][dt][1] * O[0][dt][1]) + (O[0][dt][2] * O[0][dt][2] + O[0][dt][3] * O[0][dt][3]); }
;         ss += __shfl_xor(ss, 16); ss += __shfl_xor(ss, 32);
.LBB0_616:
	global_load_dwordx4 v[48:51], v[218:219], off
	global_load_dwordx4 v[52:55], v[218:219], off offset:64
	global_load_dwordx4 v[56:59], v[218:219], off offset:128
	global_load_dwordx4 v[60:63], v[218:219], off offset:192
	global_load_dwordx4 v[64:67], v[218:219], off offset:256
	global_load_dwordx4 v[68:71], v[218:219], off offset:320
	global_load_dwordx4 v[72:75], v[218:219], off offset:384
	global_load_dwordx4 v[76:79], v[218:219], off offset:448
	ds_bpermute_b32 v0, v211, v235
	ds_bpermute_b32 v1, v211, v234
	s_lshl_b32 s6, s34, 1
	v_mov_b32_e32 v227, v5
	s_add_i32 s17, s17, s96
	s_waitcnt lgkmcnt(1)
	v_add_f32_e32 v0, v235, v0
	ds_bpermute_b32 v2, v238, v0
	s_waitcnt lgkmcnt(1)
	v_add_f32_e32 v1, v234, v1
	ds_bpermute_b32 v3, v238, v1
	s_cmpk_lt_i32 s17, 0x200
	s_waitcnt lgkmcnt(1)
	v_add_f32_e32 v0, v0, v2
	v_rcp_f32_e32 v0, v0
	s_waitcnt lgkmcnt(0)
	v_add_f32_e32 v1, v1, v3
	v_rcp_f32_e32 v4, v1
	v_mul_f32_e32 v6, v248, v0
	v_pk_mul_f32 v[0:1], v[188:189], v[6:7] op_sel_hi:[1,0]
	v_pk_mul_f32 v[8:9], v[176:177], v[6:7] op_sel_hi:[1,0]
	v_pk_mul_f32 v[2:3], v[190:191], v[6:7] op_sel_hi:[1,0]
	v_pk_mul_f32 v[10:11], v[178:179], v[6:7] op_sel_hi:[1,0]
	v_pk_fma_f32 v[14:15], v[184:185], v[4:5], v[0:1] op_sel_hi:[1,0,1] neg_lo:[0,0,1] neg_hi:[0,0,1]
	v_pk_fma_f32 v[8:9], v[180:181], v[4:5], v[8:9] op_sel_hi:[1,0,1] neg_lo:[0,0,1] neg_hi:[0,0,1]
	v_pk_fma_f32 v[12:13], v[186:187], v[4:5], v[2:3] op_sel_hi:[1,0,1] neg_lo:[0,0,1] neg_hi:[0,0,1]
	v_pk_fma_f32 v[10:11], v[182:183], v[4:5], v[10:11] op_sel_hi:[1,0,1] neg_lo:[0,0,1] neg_hi:[0,0,1]
	v_mov_b32_e32 v2, v15
	v_mov_b32_e32 v3, v9
	v_mov_b32_e32 v0, v14
	v_mov_b32_e32 v1, v8
	v_pk_mul_f32 v[2:3], v[2:3], v[2:3]
	v_mov_b32_e32 v16, v13
	v_mov_b32_e32 v17, v11
	v_pk_fma_f32 v[0:1], v[0:1], v[0:1], v[2:3]
	v_mov_b32_e32 v2, v12
	v_mov_b32_e32 v3, v10
	v_pk_mul_f32 v[16:17], v[16:17], v[16:17]
	v_pk_mul_f32 v[32:33], v[136:137], v[6:7] op_sel_hi:[1,0]
	v_pk_fma_f32 v[2:3], v[2:3], v[2:3], v[16:17]
	v_pk_mul_f32 v[34:35], v[138:139], v[6:7] op_sel_hi:[1,0]
	v_pk_add_f32 v[0:1], v[0:1], v[2:3]
	v_pk_mul_f32 v[2:3], v[160:161], v[6:7] op_sel_hi:[1,0]
	v_pk_add_f32 v[16:17], v[0:1], v[0:1] op_sel_hi:[0,1]
	v_pk_mul_f32 v[0:1], v[162:163], v[6:7] op_sel_hi:[1,0]
	v_pk_fma_f32 v[18:19], v[164:165], v[4:5], v[2:3] op_sel_hi:[1,0,1] neg_lo:[0,0,1] neg_hi:[0,0,1]
	v_pk_fma_f32 v[20:21], v[166:167], v[4:5], v[0:1] op_sel_hi:[1,0,1] neg_lo:[0,0,1] neg_hi:[0,0,1]
	v_pk_mul_f32 v[22:23], v[20:21], v[20:21]
	v_pk_mul_f32 v[24:25], v[18:19], v[18:19]
	v_pk_fma_f32 v[34:35], v[142:143], v[4:5], v[34:35] op_sel_hi:[1,0,1] neg_lo:[0,0,1] neg_hi:[0,0,1]
	v_pk_mov_b32 v[26:27], v[24:25], v[22:23] op_sel:[1,0]
	v_mov_b32_e32 v25, v23
	v_pk_add_f32 v[22:23], v[26:27], v[24:25]
	v_pk_mul_f32 v[24:25], v[144:145], v[6:7] op_sel_hi:[1,0]
	v_pk_mul_f32 v[26:27], v[146:147], v[6:7] op_sel_hi:[1,0]
	v_pk_fma_f32 v[24:25], v[148:149], v[4:5], v[24:25] op_sel_hi:[1,0,1] neg_lo:[0,0,1] neg_hi:[0,0,1]
	v_pk_fma_f32 v[26:27], v[150:151], v[4:5], v[26:27] op_sel_hi:[1,0,1] neg_lo:[0,0,1] neg_hi:[0,0,1]
	v_mul_f32_e32 v16, v24, v24
	v_pk_fma_f32 v[28:29], v[24:25], v[24:25], v[16:17] op_sel_hi:[1,1,0]
	v_mul_f32_e32 v16, v26, v26
	v_pk_add_f32 v[22:23], v[22:23], v[22:23] op_sel_hi:[0,1]
	v_pk_fma_f32 v[30:31], v[26:27], v[26:27], v[16:17] op_sel_hi:[1,1,0]
	v_pk_fma_f32 v[32:33], v[140:141], v[4:5], v[32:33] op_sel_hi:[1,0,1] neg_lo:[0,0,1] neg_hi:[0,0,1]
	v_mul_f32_e32 v22, v34, v34
	v_mul_f32_e32 v28, v32, v32
	v_mul_f32_e32 v30, v33, v33
	v_mul_f32_e32 v16, v35, v35
	v_pk_add_f32 v[28:29], v[28:29], v[30:31]
	v_pk_add_f32 v[16:17], v[22:23], v[16:17]
	v_pk_mul_f32 v[22:23], v[126:127], v[6:7] op_sel_hi:[1,0]
	v_pk_add_f32 v[16:17], v[28:29], v[16:17]
	v_pk_mul_f32 v[28:29], v[124:125], v[6:7] op_sel_hi:[1,0]
	v_pk_fma_f32 v[22:23], v[134:135], v[4:5], v[22:23] op_sel_hi:[1,0,1] neg_lo:[0,0,1] neg_hi:[0,0,1]
	v_pk_fma_f32 v[28:29], v[132:133], v[4:5], v[28:29] op_sel_hi:[1,0,1] neg_lo:[0,0,1] neg_hi:[0,0,1]
	v_pk_mul_f32 v[30:31], v[22:23], v[22:23]
	v_pk_mul_f32 v[36:37], v[28:29], v[28:29]
	v_pk_add_f32 v[16:17], v[16:17], v[16:17] op_sel_hi:[0,1]
	v_pk_mov_b32 v[38:39], v[36:37], v[30:31] op_sel:[1,0]
	v_mov_b32_e32 v37, v31
	v_pk_add_f32 v[30:31], v[38:39], v[36:37]
	v_pk_mul_f32 v[36:37], v[116:117], v[6:7] op_sel_hi:[1,0]
	v_pk_mul_f32 v[38:39], v[118:119], v[6:7] op_sel_hi:[1,0]
	v_pk_fma_f32 v[36:37], v[120:121], v[4:5], v[36:37] op_sel_hi:[1,0,1] neg_lo:[0,0,1] neg_hi:[0,0,1]
	v_pk_fma_f32 v[38:39], v[122:123], v[4:5], v[38:39] op_sel_hi:[1,0,1] neg_lo:[0,0,1] neg_hi:[0,0,1]
	v_mul_f32_e32 v16, v36, v36
	v_pk_fma_f32 v[40:41], v[36:37], v[36:37], v[16:17] op_sel_hi:[1,1,0]
	v_mul_f32_e32 v16, v38, v38
	v_pk_mul_f32 v[44:45], v[100:101], v[6:7] op_sel_hi:[1,0]
	v_pk_mul_f32 v[6:7], v[102:103], v[6:7] op_sel_hi:[1,0]
	v_pk_add_f32 v[30:31], v[30:31], v[30:31] op_sel_hi:[0,1]
	v_pk_fma_f32 v[42:43], v[38:39], v[38:39], v[16:17] op_sel_hi:[1,1,0]
	v_pk_fma_f32 v[6:7], v[110:111], v[4:5], v[6:7] op_sel_hi:[1,0,1] neg_lo:[0,0,1] neg_hi:[0,0,1]
	v_pk_fma_f32 v[44:45], v[108:109], v[4:5], v[44:45] op_sel_hi:[1,0,1] neg_lo:[0,0,1] neg_hi:[0,0,1]
	v_mul_f32_e32 v30, v6, v6
	v_mul_f32_e32 v40, v44, v44
	v_mul_f32_e32 v42, v45, v45
	v_mul_f32_e32 v16, v7, v7
	v_pk_add_f32 v[40:41], v[40:41], v[42:43]
	v_pk_add_f32 v[16:17], v[30:31], v[16:17]
	s_nop 0
	v_pk_add_f32 v[16:17], v[40:41], v[16:17]
	s_nop 0
	v_add_f32_e32 v4, v16, v17
	ds_bpermute_b32 v16, v211, v4
	s_waitcnt lgkmcnt(0)
; __device__ __forceinline__ unsigned pk2(float lo, float hi) { return pg8::cvt_pk_bf16(lo, hi); }
; __device__ __forceinline__ void attn_phase(const Params& P, LAS unsigned char* lds, int tid, int wid, int lane) {
;     ...
;         const float rstd = 0.8f * __builtin_amdgcn_rsqf(ss * (1.0f / 128.0f) + 1e-6f);
;         bf16* orow = CAT + (size_t)(b * SEQ + qframe) * 1024 + hh * 128 + 4 * fq; const float* og = P.in[I_AON] + 4 * fq;
; #pragma unroll
;         for (int dt = 0; dt < 8; ++dt) { const f32x4 g = *(const f32x4*)(og + 16 * dt); u32x2 o; o.x = pk2(O[0][dt][0] * rstd * g[0], O[0][dt][1] * rstd * g[1]); o.y = pk2(O[0][dt][2] * rstd * g[2], O[0][dt][3] * rstd * g[3]);
;             *(u32x2*)(orow + 16 * dt) = o; }
	v_add_f32_e32 v4, v4, v16
	ds_bpermute_b32 v16, v238, v4
	s_waitcnt lgkmcnt(0)
	v_add_f32_e32 v4, v4, v16
	v_fmamk_f32 v4, v4, 0x3c000000, v250
	v_rsq_f32_e32 v4, v4
	v_lshlrev_b64 v[16:17], 11, v[228:229]
	v_lshl_add_u64 v[16:17], s[12:13], 0, v[16:17]
	v_lshl_add_u64 v[16:17], v[16:17], 0, s[6:7]
	v_mul_f32_e32 v4, 0x3f4ccccd, v4
	v_pk_mul_f32 v[14:15], v[14:15], v[4:5] op_sel_hi:[1,0]
	v_pk_mul_f32 v[12:13], v[12:13], v[4:5] op_sel_hi:[1,0]
	v_lshl_add_u64 v[16:17], v[16:17], 0, v[226:227]
	v_pk_mul_f32 v[8:9], v[8:9], v[4:5] op_sel_hi:[1,0]
	v_pk_mul_f32 v[10:11], v[10:11], v[4:5] op_sel_hi:[1,0]
	s_waitcnt vmcnt(0)
	v_pk_mul_f32 v[0:1], v[48:49], v[14:15]
	v_pk_mul_f32 v[2:3], v[50:51], v[12:13]
	v_cvt_pk_bf16_f32 v0, v0, v1
	v_cvt_pk_bf16_f32 v1, v2, v3
	global_store_dwordx2 v[16:17], v[0:1], off
	v_pk_mul_f32 v[6:7], v[6:7], v[4:5] op_sel_hi:[1,0]
	v_pk_mul_f32 v[0:1], v[52:53], v[8:9]
	v_pk_mul_f32 v[2:3], v[54:55], v[10:11]
	v_cvt_pk_bf16_f32 v0, v0, v1
	v_cvt_pk_bf16_f32 v1, v2, v3
	global_store_dwordx2 v[16:17], v[0:1], off offset:32
	v_pk_mul_f32 v[8:9], v[18:19], v[4:5] op_sel_hi:[1,0]
	v_pk_mul_f32 v[10:11], v[20:21], v[4:5] op_sel_hi:[1,0]
	v_pk_mul_f32 v[0:1], v[56:57], v[8:9]
	v_pk_mul_f32 v[2:3], v[58:59], v[10:11]
	v_cvt_pk_bf16_f32 v0, v0, v1
	v_cvt_pk_bf16_f32 v1, v2, v3
	global_store_dwordx2 v[16:17], v[0:1], off offset:64
	v_pk_mul_f32 v[8:9], v[24:25], v[4:5] op_sel_hi:[1,0]
	v_pk_mul_f32 v[10:11], v[26:27], v[4:5] op_sel_hi:[1,0]
	v_pk_mul_f32 v[0:1], v[60:61], v[8:9]
	v_pk_mul_f32 v[2:3], v[62:63], v[10:11]
	v_cvt_pk_bf16_f32 v0, v0, v1
	v_cvt_pk_bf16_f32 v1, v2, v3
	global_store_dwordx2 v[16:17], v[0:1], off offset:96
	v_pk_mul_f32 v[8:9], v[32:33], v[4:5] op_sel_hi:[1,0]
	v_pk_mul_f32 v[10:11], v[34:35], v[4:5] op_sel_hi:[1,0]
	v_pk_mul_f32 v[0:1], v[64:65], v[8:9]
	v_pk_mul_f32 v[2:3], v[66:67], v[10:11]
	v_cvt_pk_bf16_f32 v0, v0, v1
	v_cvt_pk_bf16_f32 v1, v2, v3
	global_store_dwordx2 v[16:17], v[0:1], off offset:128
	v_pk_mul_f32 v[8:9], v[28:29], v[4:5] op_sel_hi:[1,0]
	v_pk_mul_f32 v[10:11], v[22:23], v[4:5] op_sel_hi:[1,0]
	v_pk_mul_f32 v[0:1], v[68:69], v[8:9]
	v_pk_mul_f32 v[2:3], v[70:71], v[10:11]
	v_cvt_pk_bf16_f32 v0, v0, v1
	v_cvt_pk_bf16_f32 v1, v2, v3
	global_store_dwordx2 v[16:17], v[0:1], off offset:160
	v_pk_mul_f32 v[8:9], v[36:37], v[4:5] op_sel_hi:[1,0]
	v_pk_mul_f32 v[10:11], v[38:39], v[4:5] op_sel_hi:[1,0]
	v_pk_mul_f32 v[0:1], v[72:73], v[8:9]
	v_pk_mul_f32 v[2:3], v[74:75], v[10:11]
	v_cvt_pk_bf16_f32 v0, v0, v1
	v_cvt_pk_bf16_f32 v1, v2, v3
	global_store_dwordx2 v[16:17], v[0:1], off offset:192
	v_pk_mul_f32 v[8:9], v[44:45], v[4:5] op_sel_hi:[1,0]
	v_pk_mul_f32 v[2:3], v[78:79], v[6:7]
	v_pk_mul_f32 v[0:1], v[76:77], v[8:9]
	s_nop 0
	v_cvt_pk_bf16_f32 v0, v0, v1
	v_cvt_pk_bf16_f32 v1, v2, v3
	global_store_dwordx2 v[16:17], v[0:1], off offset:224
	s_cbranch_scc0 .LBB0_685
